# gdn_prep: next-item gate-scalar loads issued first and through SGPR-base addressing (64-bit VGPR address mode issues much slower for scattered lanes)
# baseline (speedup 1.0000x reference)
; DI void phase_gdn_prep(const Params& p, int l, char* smem) {
;     ...
;         if (tid < 64) { pbb = p.side[(row0_ + tid) * 12 + h_]; paa = p.side[(row0_ + tid) * 12 + 6 + h_]; }
;     ...
;         {
;             const int t = tid >> 2, part = tid & 3;
;             const float bt = sbeta[t], be = bt * __expf(sgc[t]);
; #pragma unroll
;             for (int j = 0; j < 16; ++j) { sv[t * 65 + part * 16 + j] *= bt; sk[t * 65 + part * 16 + j] *= be; }
;         }
;         __syncthreads();
;         { const int nxt = item + (int)gridDim.x; prefetch(nxt < 3072 ? nxt : item); }
.LBB0_313:
	v_mov_b32_e32 v6, v96
	v_mul_f32_e32 v0, v0, v185
	v_mul_f32_e32 v1, v1, v185
	v_mul_f32_e32 v2, v2, v185
	v_mul_f32_e32 v3, v3, v185
	v_mul_f32_e32 v0, v0, v12
	v_mul_f32_e32 v1, v1, v4
	v_mul_f32_e32 v2, v2, v5
	v_mul_f32_e32 v3, v3, v6
	v_cndmask_b32_e64 v0, 0, v0, s[16:17]
	v_cndmask_b32_e64 v1, 0, v1, s[20:21]
	v_cndmask_b32_e64 v2, 0, v2, s[24:25]
	v_mul_f32_e32 v5, v30, v5
	v_mul_f32_e32 v7, v28, v12
	v_mul_f32_e32 v4, v29, v4
	v_cndmask_b32_e64 v3, 0, v3, s[28:29]
	v_mul_f32_e32 v6, v31, v6
	ds_write_b128 v145, v[0:3] offset:50112
	v_cvt_pk_bf16_f32 v0, v7, v4
	v_cvt_pk_bf16_f32 v1, v5, v6
	global_store_dwordx2 v[20:21], v[0:1], off offset:72
	v_add_u32_e32 v1, 0x8200, v118
	ds_read_b32 v2, v74
	ds_read_b32 v0, v71
	ds_read2_b32 v[4:5], v1 offset0:0 offset1:1
	ds_read2_b32 v[6:7], v1 offset0:2 offset1:3
	ds_read2_b32 v[8:9], v1 offset0:4 offset1:5
	ds_read2_b32 v[10:11], v1 offset0:6 offset1:7
	ds_read2_b32 v[12:13], v1 offset0:8 offset1:9
	ds_read2_b32 v[14:15], v1 offset0:10 offset1:11
	ds_read2_b32 v[16:17], v1 offset0:12 offset1:13
	ds_read2_b32 v[18:19], v1 offset0:14 offset1:15
	v_readlane_b32 s4, v249, 16
	s_add_i32 s30, s86, s4
	s_cmpk_gt_i32 s30, 0xbff
	v_readlane_b32 s5, v249, 17
	s_cselect_b64 s[90:91], -1, 0
	s_cmpk_lt_i32 s30, 0xc00
	s_cselect_b32 s5, s30, s86
	s_ashr_i32 s6, s5, 8
	s_mul_hi_i32 s4, s6, 0x2aaaaaab
	s_lshr_b32 s7, s4, 31
	s_add_i32 s4, s4, s7
	s_mul_i32 s7, s4, 6
	s_lshl_b32 s5, s5, 6
	s_sub_i32 s86, s6, s7
	s_and_b32 s6, s5, 0x3fc0
	s_ashr_i32 s5, s4, 31
	s_sub_i32 s8, 2, s6
	s_lshl_b64 s[92:93], s[4:5], 14
	s_lshl_b32 s94, s86, 6
	v_cmp_lt_i32_e32 vcc, s8, v46
	s_or_b32 s92, s92, s6
	s_ashr_i32 s95, s94, 31
	s_and_b64 s[96:97], s[42:43], vcc
	s_waitcnt lgkmcnt(0)
	ds_read2_b32 v[20:21], v59 offset0:0 offset1:1
	ds_read2_b32 v[22:23], v59 offset0:2 offset1:3
	ds_read2_b32 v[24:25], v59 offset0:4 offset1:5
	ds_read2_b32 v[26:27], v59 offset0:6 offset1:7
	ds_read2_b32 v[28:29], v59 offset0:8 offset1:9
	ds_read2_b32 v[30:31], v59 offset0:10 offset1:11
	ds_read2_b32 v[32:33], v59 offset0:12 offset1:13
	ds_read2_b32 v[34:35], v59 offset0:14 offset1:15
	v_mul_f32_e32 v0, 0x3fb8aa3b, v0
	v_exp_f32_e32 v0, v0
	v_pk_mul_f32 v[4:5], v[2:3], v[4:5] op_sel_hi:[0,1]
	v_pk_mul_f32 v[6:7], v[2:3], v[6:7] op_sel_hi:[0,1]
	v_pk_mul_f32 v[8:9], v[2:3], v[8:9] op_sel_hi:[0,1]
	v_pk_mul_f32 v[10:11], v[2:3], v[10:11] op_sel_hi:[0,1]
	v_pk_mul_f32 v[12:13], v[2:3], v[12:13] op_sel_hi:[0,1]
	v_pk_mul_f32 v[14:15], v[2:3], v[14:15] op_sel_hi:[0,1]
	v_pk_mul_f32 v[16:17], v[2:3], v[16:17] op_sel_hi:[0,1]
	v_pk_mul_f32 v[18:19], v[2:3], v[18:19] op_sel_hi:[0,1]
	v_mul_f32_e32 v0, v2, v0
	s_waitcnt lgkmcnt(0)
	ds_write2_b32 v1, v4, v5 offset0:0 offset1:1
	ds_write2_b32 v1, v6, v7 offset0:2 offset1:3
	ds_write2_b32 v1, v8, v9 offset0:4 offset1:5
	ds_write2_b32 v1, v10, v11 offset0:6 offset1:7
	ds_write2_b32 v1, v12, v13 offset0:8 offset1:9
	ds_write2_b32 v1, v14, v15 offset0:10 offset1:11
	ds_write2_b32 v1, v16, v17 offset0:12 offset1:13
	ds_write2_b32 v1, v18, v19 offset0:14 offset1:15
	v_pk_mul_f32 v[20:21], v[0:1], v[20:21] op_sel_hi:[0,1]
	v_pk_mul_f32 v[22:23], v[0:1], v[22:23] op_sel_hi:[0,1]
	v_pk_mul_f32 v[24:25], v[0:1], v[24:25] op_sel_hi:[0,1]
	v_pk_mul_f32 v[26:27], v[0:1], v[26:27] op_sel_hi:[0,1]
	v_pk_mul_f32 v[28:29], v[0:1], v[28:29] op_sel_hi:[0,1]
	v_pk_mul_f32 v[30:31], v[0:1], v[30:31] op_sel_hi:[0,1]
	v_pk_mul_f32 v[32:33], v[0:1], v[32:33] op_sel_hi:[0,1]
	v_pk_mul_f32 v[34:35], v[0:1], v[34:35] op_sel_hi:[0,1]
	ds_write2_b32 v59, v20, v21 offset0:0 offset1:1
	ds_write2_b32 v59, v22, v23 offset0:2 offset1:3
	ds_write2_b32 v59, v24, v25 offset0:4 offset1:5
	ds_write2_b32 v59, v26, v27 offset0:6 offset1:7
	ds_write2_b32 v59, v28, v29 offset0:8 offset1:9
	ds_write2_b32 v59, v30, v31 offset0:10 offset1:11
	ds_write2_b32 v59, v32, v33 offset0:12 offset1:13
	ds_write2_b32 v59, v34, v35 offset0:14 offset1:15
	v_mov_b32_e32 v24, 0
	v_mov_b32_e32 v25, 0
	v_mov_b32_e32 v26, 0
	v_mov_b32_e32 v27, 0
	s_waitcnt lgkmcnt(0)
	s_barrier
	s_and_saveexec_b64 s[4:5], s[38:39]
	s_cbranch_execz .Lpbb_skip
	v_readlane_b32 s52, v250, 51
	v_lshl_add_u64 v[36:37], s[92:93], 0, v[40:41]
	v_readlane_b32 s64, v250, 63
	v_readlane_b32 s65, v249, 0
	s_ashr_i32 s87, s86, 31
	v_readlane_b32 s53, v250, 52
	v_add_u32_e32 v36, s92, v40
	v_mul_u32_u24_e32 v36, 48, v36
	s_lshl_b32 s2, s86, 2
	s_nop 1
	v_add_u32_e32 v36, s2, v36
	global_load_dword v55, v36, s[64:65]
	global_load_dword v49, v36, s[64:65] offset:24
	v_readlane_b32 s54, v250, 53
	v_readlane_b32 s55, v250, 54
	v_readlane_b32 s56, v250, 55
	v_readlane_b32 s57, v250, 56
	v_readlane_b32 s58, v250, 57
	v_readlane_b32 s59, v250, 58
	v_readlane_b32 s60, v250, 59
	v_readlane_b32 s61, v250, 60
	v_readlane_b32 s62, v250, 61
	v_readlane_b32 s63, v250, 62
	v_readlane_b32 s66, v249, 1
	v_readlane_b32 s67, v249, 2
; DI void phase_gdn_prep(const Params& p, int l, char* smem) {
;     ...
;     auto prefetch = [&](int it) {
;         const int chunk_ = it & 255, bh_ = it >> 8, h_ = bh_ % 6, b_ = bh_ / 6;
;         const int tb0_ = chunk_ * 64; const size_t row0_ = (size_t)b_ * T_ + tb0_;
; #pragma unroll
;         for (int part = 0; part < 3; ++part)
; #pragma unroll
;             for (int k = 0; k < 3; ++k) {
;                 const int c = tid + 256 * k, r = c >> 3, cc = c & 7;
;                 const bool ok = c < 67 * 8 && tb0_ + r - 3 >= 0;
;                 const bf16_t* src = p.proj + (row0_ + (ok ? r : 3) - 3) * DINP + part * 384 + h_ * 64 + cc * 8;
;                 const u32x4 v = *(const u32x4*)src;
;                 raw[part * 3 + k] = ok ? v : (u32x4){0u, 0u, 0u, 0u};
;             }
.Lpbb_skip:
	s_or_b64 exec, exec, s[4:5]
	v_cmp_lt_i32_e32 vcc, s8, v50
	s_and_b64 s[4:5], s[44:45], vcc
	v_cmp_lt_i32_e32 vcc, s8, v52
	s_and_b64 s[6:7], s[46:47], vcc
	v_readlane_b32 s56, v250, 55
	v_readlane_b32 s57, v250, 56
	s_lshl_b32 s2, s94, 1
	v_lshlrev_b32_e32 v188, 1, v48
	v_mov_b32_e32 v0, 0
	v_mov_b32_e32 v1, 0
	v_mov_b32_e32 v2, 0
	v_mov_b32_e32 v3, 0
	v_mov_b32_e32 v4, 0
	v_mov_b32_e32 v5, 0
	v_mov_b32_e32 v6, 0
	v_mov_b32_e32 v7, 0
	v_mov_b32_e32 v8, 0
	v_mov_b32_e32 v9, 0
	v_mov_b32_e32 v10, 0
	v_mov_b32_e32 v11, 0
	v_mov_b32_e32 v12, 0
	v_mov_b32_e32 v13, 0
	v_mov_b32_e32 v14, 0
	v_mov_b32_e32 v15, 0
	v_mov_b32_e32 v16, 0
	v_mov_b32_e32 v17, 0
	v_mov_b32_e32 v18, 0
	v_mov_b32_e32 v19, 0
	v_mov_b32_e32 v20, 0
	v_mov_b32_e32 v21, 0
	v_mov_b32_e32 v22, 0
	v_mov_b32_e32 v23, 0
	v_mov_b32_e32 v24, 0
	v_mov_b32_e32 v25, 0
	v_mov_b32_e32 v26, 0
	v_mov_b32_e32 v27, 0
	v_mov_b32_e32 v28, 0
	v_mov_b32_e32 v29, 0
	v_mov_b32_e32 v30, 0
	v_mov_b32_e32 v31, 0
	v_mov_b32_e32 v32, 0
	v_mov_b32_e32 v33, 0
	v_mov_b32_e32 v34, 0
	v_mov_b32_e32 v35, 0
	v_add_u32_e32 v108, s92, v46
	v_add_u32_e32 v108, -3, v108
	v_mul_u32_u24_e32 v108, 0x1800, v108
	v_add3_u32 v108, v108, s2, v188
	v_add_u32_e32 v109, s92, v50
	v_add_u32_e32 v109, -3, v109
	v_mul_u32_u24_e32 v109, 0x1800, v109
	v_add3_u32 v109, v109, s2, v188
	v_add_u32_e32 v110, s92, v52
	v_add_u32_e32 v110, -3, v110
	v_mul_u32_u24_e32 v110, 0x1800, v110
	v_add3_u32 v110, v110, s2, v188
	s_and_saveexec_b64 s[98:99], s[96:97]
	global_load_dwordx4 v[24:27], v108, s[56:57]
	global_load_dwordx4 v[12:15], v108, s[56:57] offset:768
	global_load_dwordx4 v[0:3], v108, s[56:57] offset:1536
	s_mov_b64 exec, s[98:99]
	s_and_saveexec_b64 s[98:99], s[4:5]
	global_load_dwordx4 v[28:31], v109, s[56:57]
	global_load_dwordx4 v[16:19], v109, s[56:57] offset:768
	global_load_dwordx4 v[4:7], v109, s[56:57] offset:1536
	s_mov_b64 exec, s[98:99]
	s_and_saveexec_b64 s[98:99], s[6:7]
	global_load_dwordx4 v[32:35], v110, s[56:57]
	global_load_dwordx4 v[20:23], v110, s[56:57] offset:768
	global_load_dwordx4 v[8:11], v110, s[56:57] offset:1536
	s_mov_b64 exec, s[98:99]
	v_readlane_b32 s52, v250, 51
	v_readlane_b32 s53, v250, 52
	v_readlane_b32 s54, v250, 53
	v_readlane_b32 s55, v250, 54
	v_readlane_b32 s58, v250, 57
	v_readlane_b32 s59, v250, 58
	v_readlane_b32 s60, v250, 59
	v_readlane_b32 s61, v250, 60
	v_readlane_b32 s62, v250, 61
	v_readlane_b32 s63, v250, 62
	v_readlane_b32 s64, v250, 63
	v_readlane_b32 s65, v249, 0
	v_readlane_b32 s66, v249, 1
	v_readlane_b32 s67, v249, 2
